# V-plane GEMM units run with operand pointers exchanged and a hand-written epilogue that stores per-tile transposed V images; attention reads V fragments with 32 ds_read_b128 per tile (no extra pass or
# speedup vs baseline: 1.0052x; 1.0052x over previous
.LBB0_176:
	s_lshl_b32 s38, s89, 10
	v_lshl_add_u32 v0, v8, 4, s38
	v_ashrrev_i32_e32 v1, 31, v0
	v_lshrrev_b32_e32 v1, 22, v1
	v_add_u32_e32 v1, v0, v1
	v_ashrrev_i32_e32 v9, 10, v1
	v_mul_i32_i24_e32 v1, 0x400, v9
	v_sub_u32_e32 v1, v0, v1
	v_lshrrev_b32_e32 v2, 4, v1
	v_bitop3_b32 v1, v2, v1, 32 bitop3:0x6c
	v_ashrrev_i32_e32 v3, 31, v1
	v_lshrrev_b32_e32 v3, 26, v3
	v_add_u32_e32 v3, v1, v3
	v_lshlrev_b32_e32 v2, 3, v9
	v_ashrrev_i32_e32 v10, 6, v3
	v_and_b32_e32 v3, 0xc0, v3
	v_and_b32_e32 v2, -16, v2
	v_sub_u32_e32 v1, v1, v3
	v_mov_b32_e32 v3, 1
	v_add_u32_e32 v2, v10, v2
	v_ashrrev_i16_sdwa v1, v3, sext(v1) dst_sel:DWORD dst_unused:UNUSED_PAD src0_sel:DWORD src1_sel:BYTE_0
	s_ashr_i32 s0, s5, 3
	v_lshlrev_b32_e32 v4, 5, v9
	v_bfe_i32 v11, v1, 0, 16
	v_lshlrev_b32_e32 v1, 1, v2
	s_waitcnt lgkmcnt(0)
	v_lshrrev_b32_e32 v5, 2, v2
	v_and_b32_e32 v6, 3, v10
	s_mov_b32 s5, 0x7ffe0
	v_and_b32_e32 v4, 32, v4
	v_and_b32_e32 v1, 24, v1
	v_and_b32_e32 v5, 4, v5
	v_and_or_b32 v6, v2, s5, v6
	v_or3_b32 v1, v6, v5, v1
	v_add_lshl_u32 v4, v4, v11, 1
	v_add_u32_e32 v0, 0x2000, v0
	v_lshl_add_u32 v130, v1, 13, v4
	v_ashrrev_i32_e32 v1, 31, v0
	v_lshrrev_b32_e32 v1, 22, v1
	v_add_u32_e32 v1, v0, v1
	v_ashrrev_i32_e32 v12, 10, v1
	v_mul_i32_i24_e32 v1, 0x400, v12
	v_sub_u32_e32 v0, v0, v1
	v_lshrrev_b32_e32 v1, 4, v0
	v_bitop3_b32 v0, v1, v0, 32 bitop3:0x6c
	v_lshl_add_u32 v128, v2, 13, v4
	v_ashrrev_i32_e32 v2, 31, v0
	v_lshrrev_b32_e32 v2, 26, v2
	v_add_u32_e32 v2, v0, v2
	s_lshr_b32 s1, s87, 8
	v_ashrrev_i32_e32 v13, 6, v2
	v_and_b32_e32 v2, 0xffc0, v2
	v_sub_u32_e32 v0, v0, v2
	s_add_u32 s39, s64, 0x8000000
	v_lshrrev_b16_e32 v2, 7, v0
	s_addc_u32 s48, s65, 0
	s_add_i32 s0, s4, s0
	v_lshlrev_b32_e32 v1, 3, v12
	v_and_b32_e32 v2, 1, v2
	s_ashr_i32 s4, s0, 31
	v_and_b32_e32 v1, -16, v1
	v_add_u16_e32 v0, v0, v2
	s_lshr_b32 s4, s4, 24
	v_add_u32_e32 v1, v13, v1
	v_ashrrev_i16_sdwa v0, v3, sext(v0) dst_sel:DWORD dst_unused:UNUSED_PAD src0_sel:DWORD src1_sel:BYTE_0
	v_and_b32_e32 v3, 3, v13
	s_add_i32 s4, s0, s4
	v_and_or_b32 v3, v1, s5, v3
	s_ashr_i32 s5, s4, 8
	s_and_b32 s4, s4, 0xffffff00
	s_sub_i32 s4, s0, s4
	s_sext_i32_i16 s0, s4
	s_bfe_u32 s0, s0, 0x2001d
	s_add_i32 s6, s4, s0
	s_sext_i32_i16 s0, s6
	s_and_b32 s6, s6, 0xfffc
	s_sub_i32 s4, s4, s6
	s_lshl_b32 s5, s5, 2
	s_sext_i32_i16 s4, s4
	s_lshr_b32 s0, s0, 2
	s_add_i32 s28, s5, s4
	s_ashr_i32 s29, s28, 31
	s_bfe_i64 s[6:7], s[0:1], 0x100000
	s_lshl_b64 s[4:5], s[28:29], 21
	s_lshl_b64 s[6:7], s[6:7], 21
	s_add_u32 s34, s64, s6
	v_lshlrev_b32_e32 v4, 5, v12
	v_bfe_i32 v14, v0, 0, 16
	v_lshlrev_b32_e32 v0, 1, v1
	v_lshrrev_b32_e32 v2, 2, v1
	s_addc_u32 s35, s65, s7
	s_add_u32 s30, s39, s4
	s_addc_u32 s31, s48, s5
	s_lshr_b32 s56, s6, 21
	s_sub_i32 s56, s56, 32
	s_cmp_lt_u32 s56, 16
	s_cbranch_scc0 .Lp2_noswap0
	s_mov_b64 s[54:55], s[34:35]
	s_mov_b64 s[34:35], s[30:31]
	s_mov_b64 s[30:31], s[54:55]
.Lp2_noswap0:
	s_add_i32 s49, s38, 0
	v_and_b32_e32 v4, 32, v4
	v_and_b32_e32 v0, 24, v0
	v_and_b32_e32 v2, 4, v2
	s_add_i32 m0, s49, 0x10000
	v_or3_b32 v0, v3, v2, v0
	v_add_lshl_u32 v2, v4, v14, 1
	global_load_lds_dwordx4 v130, s[34:35]
	s_add_i32 m0, s49, 0x12000
	v_lshl_add_u32 v134, v0, 13, v2
	s_add_u32 s6, s34, 0x100000
	global_load_lds_dwordx4 v134, s[34:35]
	s_addc_u32 s7, s35, 0
	s_add_i32 m0, s49, 0x14000
	v_lshl_add_u32 v132, v1, 13, v2
	global_load_lds_dwordx4 v130, s[6:7]
	s_add_i32 m0, s49, 0x16000
	s_add_i32 s54, s49, 0x2000
	global_load_lds_dwordx4 v134, s[6:7]
	s_mov_b32 m0, s49
	s_add_u32 s4, s30, 0x100000
	global_load_lds_dwordx4 v128, s[30:31]
	s_mov_b32 m0, s54
	s_addc_u32 s5, s31, 0
	s_add_i32 s55, s49, 0x4000
	global_load_lds_dwordx4 v132, s[30:31]
	s_mov_b32 m0, s55
	s_add_i32 s56, s49, 0x6000
	global_load_lds_dwordx4 v128, s[4:5]
	s_mov_b32 m0, s56
	v_mov_b32_e32 v131, 0
	global_load_lds_dwordx4 v132, s[4:5]
	v_mov_b32_e32 v135, v131
	v_mov_b32_e32 v129, v131
	v_mov_b32_e32 v133, v131
	s_cmp_eq_u32 s1, 1
	s_mov_b32 s57, 0
	v_lshl_add_u64 v[6:7], s[34:35], 0, v[130:131]
	v_lshl_add_u64 v[2:3], s[34:35], 0, v[134:135]
	s_mov_b64 s[4:5], 0x100000
	v_lshl_add_u64 v[0:1], s[30:31], 0, v[128:129]
	s_cselect_b64 s[6:7], -1, 0
	s_cmp_lg_u32 s1, 1
	v_lshl_add_u64 v[4:5], s[30:31], 0, v[132:133]
	s_cbranch_scc1 .LBB0_178
	s_barrier

.LBB0_187:
	v_lshl_add_u32 v226, s28, 8, v146
	v_ashrrev_i32_e32 v227, 31, v226
	v_lshl_add_u64 v[226:227], v[226:227], 2, s[8:9]
	global_load_dword v228, v[226:227], off
	global_load_dword v229, v[226:227], off offset:64
	global_load_dword v230, v[226:227], off offset:128
	global_load_dword v231, v[226:227], off offset:192
	global_load_dword v232, v[226:227], off offset:512
	global_load_dword v233, v[226:227], off offset:576
	global_load_dword v234, v[226:227], off offset:640
	global_load_dword v235, v[226:227], off offset:704
	s_ashr_i32 s23, s22, 31
	s_lshl_b64 s[24:25], s[22:23], 21
	s_add_u32 s24, s39, s24
	s_addc_u32 s25, s48, s25
	s_and_b64 s[26:27], s[0:1], exec
	s_cselect_b32 s23, s25, s31
	s_cselect_b32 s73, s24, s30
	s_ashr_i32 s21, s20, 31
	s_lshl_b64 s[26:27], s[20:21], 21
	s_add_u32 s26, s64, s26
	s_addc_u32 s27, s65, s27
	s_and_b64 s[36:37], s[0:1], exec
	s_cselect_b32 s21, s27, s35
	s_cselect_b32 s74, s26, s34
	s_sub_i32 s36, s20, 32
	s_cmp_lt_u32 s36, 16
	s_cbranch_scc0 .Lp2_noswap
	s_cmp_lg_u64 s[0:1], 0
	s_cbranch_scc0 .Lp2_noswap
	s_mov_b64 s[36:37], s[24:25]
	s_mov_b64 s[24:25], s[26:27]
	s_mov_b64 s[26:27], s[36:37]
	s_mov_b32 s36, s73
	s_mov_b32 s73, s74
	s_mov_b32 s74, s36
	s_mov_b32 s36, s23
	s_mov_b32 s23, s21
	s_mov_b32 s21, s36
.Lp2_noswap:
	s_add_u32 s30, s30, 0x100080
	s_addc_u32 s31, s31, 0
	s_add_u32 s75, s34, 0x100
	v_mov_b32_e32 v0, 0
	s_addc_u32 s78, s35, 0
	s_mov_b32 s79, -2
	v_mov_b32_e32 v1, v0
	v_mov_b32_e32 v2, v0
	v_mov_b32_e32 v3, v0
	v_mov_b32_e32 v4, v0
	v_mov_b32_e32 v5, v0
	v_mov_b32_e32 v6, v0
	v_mov_b32_e32 v7, v0
	v_mov_b32_e32 v16, v0
	v_mov_b32_e32 v17, v0
	v_mov_b32_e32 v18, v0
	v_mov_b32_e32 v19, v0
	v_mov_b32_e32 v20, v0
	v_mov_b32_e32 v21, v0
	v_mov_b32_e32 v22, v0
	v_mov_b32_e32 v23, v0
	v_mov_b32_e32 v32, v0
	v_mov_b32_e32 v33, v0
	v_mov_b32_e32 v34, v0
	v_mov_b32_e32 v35, v0
	v_mov_b32_e32 v36, v0
	v_mov_b32_e32 v37, v0
	v_mov_b32_e32 v38, v0
	v_mov_b32_e32 v39, v0
	v_mov_b32_e32 v48, v0
	v_mov_b32_e32 v49, v0
	v_mov_b32_e32 v50, v0
	v_mov_b32_e32 v51, v0
	v_mov_b32_e32 v52, v0
	v_mov_b32_e32 v53, v0
	v_mov_b32_e32 v54, v0
	v_mov_b32_e32 v55, v0
	v_mov_b32_e32 v8, v0
	v_mov_b32_e32 v9, v0
	v_mov_b32_e32 v10, v0
	v_mov_b32_e32 v11, v0
	v_mov_b32_e32 v12, v0
	v_mov_b32_e32 v13, v0
	v_mov_b32_e32 v14, v0
	v_mov_b32_e32 v15, v0
	v_mov_b32_e32 v24, v0
	v_mov_b32_e32 v25, v0
	v_mov_b32_e32 v26, v0
	v_mov_b32_e32 v27, v0
	v_mov_b32_e32 v28, v0
	v_mov_b32_e32 v29, v0
	v_mov_b32_e32 v30, v0
	v_mov_b32_e32 v31, v0
	v_mov_b32_e32 v40, v0
	v_mov_b32_e32 v41, v0
	v_mov_b32_e32 v42, v0
	v_mov_b32_e32 v43, v0
	v_mov_b32_e32 v44, v0
	v_mov_b32_e32 v45, v0
	v_mov_b32_e32 v46, v0
	v_mov_b32_e32 v47, v0
	v_mov_b32_e32 v56, v0
	v_mov_b32_e32 v57, v0
	v_mov_b32_e32 v58, v0
	v_mov_b32_e32 v59, v0
	v_mov_b32_e32 v60, v0
	v_mov_b32_e32 v61, v0
	v_mov_b32_e32 v62, v0
	v_mov_b32_e32 v63, v0
	v_mov_b32_e32 v64, v0
	v_mov_b32_e32 v65, v0
	v_mov_b32_e32 v66, v0
	v_mov_b32_e32 v67, v0
	v_mov_b32_e32 v68, v0
	v_mov_b32_e32 v69, v0
	v_mov_b32_e32 v70, v0
	v_mov_b32_e32 v71, v0
	v_mov_b32_e32 v80, v0
	v_mov_b32_e32 v81, v0
	v_mov_b32_e32 v82, v0
	v_mov_b32_e32 v83, v0
	v_mov_b32_e32 v84, v0
	v_mov_b32_e32 v85, v0
	v_mov_b32_e32 v86, v0
	v_mov_b32_e32 v87, v0
	v_mov_b32_e32 v88, v0
	v_mov_b32_e32 v89, v0
	v_mov_b32_e32 v90, v0
	v_mov_b32_e32 v91, v0
	v_mov_b32_e32 v92, v0
	v_mov_b32_e32 v93, v0
	v_mov_b32_e32 v94, v0
	v_mov_b32_e32 v95, v0
	v_mov_b32_e32 v100, v0
	v_mov_b32_e32 v101, v0
	v_mov_b32_e32 v102, v0
	v_mov_b32_e32 v103, v0
	v_mov_b32_e32 v108, v0
	v_mov_b32_e32 v109, v0
	v_mov_b32_e32 v110, v0
	v_mov_b32_e32 v111, v0
	v_mov_b32_e32 v72, v0
	v_mov_b32_e32 v73, v0
	v_mov_b32_e32 v74, v0
	v_mov_b32_e32 v75, v0
	v_mov_b32_e32 v76, v0
	v_mov_b32_e32 v77, v0
	v_mov_b32_e32 v78, v0
	v_mov_b32_e32 v79, v0
	v_mov_b32_e32 v96, v0
	v_mov_b32_e32 v97, v0
	v_mov_b32_e32 v98, v0
	v_mov_b32_e32 v99, v0
	v_mov_b32_e32 v104, v0
	v_mov_b32_e32 v105, v0
	v_mov_b32_e32 v106, v0
	v_mov_b32_e32 v107, v0
	v_mov_b32_e32 v112, v0
	v_mov_b32_e32 v113, v0
	v_mov_b32_e32 v114, v0
	v_mov_b32_e32 v115, v0
	v_mov_b32_e32 v116, v0
	v_mov_b32_e32 v117, v0
	v_mov_b32_e32 v118, v0
	v_mov_b32_e32 v119, v0
	v_mov_b32_e32 v120, v0
	v_mov_b32_e32 v121, v0
	v_mov_b32_e32 v122, v0
	v_mov_b32_e32 v123, v0
	v_mov_b32_e32 v124, v0
	v_mov_b32_e32 v125, v0
	v_mov_b32_e32 v126, v0
	v_mov_b32_e32 v127, v0

.LBB0_191:
	s_sub_i32 s21, s29, 32
	s_cmp_lt_u32 s21, 16
	s_cbranch_scc1 .Lp2_vepi
	v_lshl_add_u32 v144, s28, 8, v146
	v_ashrrev_i32_e32 v145, 31, v144
	v_lshl_add_u64 v[154:155], v[144:145], 2, s[8:9]
	v_or_b32_e32 v156, 16, v144
	v_ashrrev_i32_e32 v157, 31, v156
	v_or_b32_e32 v160, 32, v144
	v_lshl_add_u64 v[158:159], v[156:157], 2, s[8:9]
	v_ashrrev_i32_e32 v161, 31, v160
	v_lshl_add_u64 v[162:163], v[160:161], 2, s[8:9]
	v_or_b32_e32 v158, 48, v144
	v_ashrrev_i32_e32 v159, 31, v158
	v_lshl_add_u64 v[162:163], v[158:159], 2, s[8:9]
	s_ashr_i32 s21, s29, 31
	s_lshr_b32 s21, s21, 28
	s_add_i32 s21, s29, s21
	s_add_i32 s23, s29, 15
	s_ashr_i32 s28, s21, 4
	s_cmp_lt_u32 s23, 31
	v_lshl_add_u32 v167, s29, 8, v148
	s_cselect_b64 vcc, -1, 0
	s_ashr_i32 s29, s28, 31
	s_lshl_b64 s[30:31], s[28:29], 27
	s_add_u32 s30, s42, s30
	s_addc_u32 s31, s43, s31
	s_lshl_b32 s21, s28, 12
	v_subrev_u32_e32 v154, s21, v167
	v_cndmask_b32_e32 v174, 1.0, v153, vcc
	v_ashrrev_i32_e32 v155, 31, v154
	v_lshlrev_b64 v[144:145], 13, v[144:145]
	v_lshl_add_u64 v[154:155], v[154:155], 1, s[30:31]
	v_lshl_add_u64 v[144:145], v[154:155], 0, v[144:145]
	v_lshlrev_b64 v[156:157], 13, v[156:157]
	v_lshl_add_u64 v[156:157], v[154:155], 0, v[156:157]
	v_lshlrev_b64 v[160:161], 13, v[160:161]
	v_lshl_add_u64 v[160:161], v[154:155], 0, v[160:161]
	s_waitcnt vmcnt(0)
	v_fmamk_f32 v162, v228, 0x39800000, v152
	v_rsq_f32_e32 v162, v162
	v_fmamk_f32 v163, v229, 0x39800000, v152
	v_fmamk_f32 v164, v230, 0x39800000, v152
	v_rsq_f32_e32 v166, v163
	v_rsq_f32_e32 v167, v164
	v_mul_f32_e32 v162, v174, v162
	v_pk_mul_f32 v[122:123], v[122:123], v[162:163] op_sel_hi:[1,0]
	v_mul_f32_e32 v166, v174, v166
	v_pk_mul_f32 v[126:127], v[126:127], v[162:163] op_sel_hi:[1,0]
	v_pk_mul_f32 v[124:125], v[124:125], v[162:163] op_sel_hi:[1,0]
	v_pk_mul_f32 v[120:121], v[120:121], v[162:163] op_sel_hi:[1,0]
	v_pk_mul_f32 v[110:111], v[110:111], v[162:163] op_sel_hi:[1,0]
	v_pk_mul_f32 v[108:109], v[108:109], v[162:163] op_sel_hi:[1,0]
	v_pk_mul_f32 v[164:165], v[102:103], v[162:163] op_sel_hi:[1,0]
	v_pk_mul_f32 v[162:163], v[100:101], v[162:163] op_sel_hi:[1,0]
	v_cvt_pk_bf16_f32 v100, v124, v125
	v_cvt_pk_bf16_f32 v101, v126, v127
	v_cvt_pk_bf16_f32 v102, v120, v121
	v_cvt_pk_bf16_f32 v103, v122, v123
	v_pk_mul_f32 v[122:123], v[88:89], v[166:167] op_sel_hi:[1,0]
	global_store_dwordx4 v[144:145], v[100:103], off
	v_cvt_pk_bf16_f32 v88, v108, v109
	v_cvt_pk_bf16_f32 v89, v110, v111
	v_pk_mul_f32 v[118:119], v[118:119], v[166:167] op_sel_hi:[1,0]
	v_pk_mul_f32 v[116:117], v[116:117], v[166:167] op_sel_hi:[1,0]
	v_pk_mul_f32 v[120:121], v[90:91], v[166:167] op_sel_hi:[1,0]
	v_cvt_pk_bf16_f32 v90, v162, v163
	v_cvt_pk_bf16_f32 v91, v164, v165
	global_store_dwordx4 v[144:145], v[88:91], off offset:256
	v_mul_f32_e32 v168, v174, v167
	v_pk_mul_f32 v[114:115], v[114:115], v[166:167] op_sel_hi:[1,0]
	v_cvt_pk_bf16_f32 v88, v116, v117
	v_cvt_pk_bf16_f32 v89, v118, v119
	v_pk_mul_f32 v[112:113], v[112:113], v[166:167] op_sel_hi:[1,0]
	v_pk_mul_f32 v[94:95], v[94:95], v[166:167] op_sel_hi:[1,0]
	v_pk_mul_f32 v[92:93], v[92:93], v[166:167] op_sel_hi:[1,0]
	v_cvt_pk_bf16_f32 v90, v112, v113
	v_cvt_pk_bf16_f32 v91, v114, v115
	global_store_dwordx4 v[156:157], v[88:91], off
	v_pk_mul_f32 v[106:107], v[106:107], v[168:169] op_sel_hi:[1,0]
	v_pk_mul_f32 v[104:105], v[104:105], v[168:169] op_sel_hi:[1,0]
	v_cvt_pk_bf16_f32 v88, v92, v93
	v_cvt_pk_bf16_f32 v89, v94, v95
	v_cvt_pk_bf16_f32 v90, v122, v123
	v_cvt_pk_bf16_f32 v91, v120, v121
	global_store_dwordx4 v[156:157], v[88:91], off offset:256
	v_pk_mul_f32 v[84:85], v[84:85], v[168:169] op_sel_hi:[1,0]
	v_pk_mul_f32 v[98:99], v[98:99], v[168:169] op_sel_hi:[1,0]
	v_cvt_pk_bf16_f32 v88, v104, v105
	v_cvt_pk_bf16_f32 v89, v106, v107
	v_pk_mul_f32 v[96:97], v[96:97], v[168:169] op_sel_hi:[1,0]
	v_pk_mul_f32 v[86:87], v[86:87], v[168:169] op_sel_hi:[1,0]
	v_cvt_pk_bf16_f32 v90, v96, v97
	v_cvt_pk_bf16_f32 v91, v98, v99
	global_store_dwordx4 v[160:161], v[88:91], off
	s_nop 1
	v_pk_mul_f32 v[88:89], v[82:83], v[168:169] op_sel_hi:[1,0]
	v_pk_mul_f32 v[82:83], v[80:81], v[168:169] op_sel_hi:[1,0]
	v_cvt_pk_bf16_f32 v80, v84, v85
	v_fmamk_f32 v84, v231, 0x39800000, v152
	v_rsq_f32_e32 v84, v84
	v_cvt_pk_bf16_f32 v81, v86, v87
	v_cvt_pk_bf16_f32 v82, v82, v83
	v_cvt_pk_bf16_f32 v83, v88, v89
	global_store_dwordx4 v[160:161], v[80:83], off offset:256
	s_nop 1
	v_mul_f32_e32 v80, v174, v84
	v_lshlrev_b64 v[82:83], 13, v[158:159]
	v_lshl_add_u64 v[82:83], v[154:155], 0, v[82:83]
	v_pk_mul_f32 v[78:79], v[78:79], v[80:81] op_sel_hi:[1,0]
	v_pk_mul_f32 v[76:77], v[76:77], v[80:81] op_sel_hi:[1,0]
	v_pk_mul_f32 v[84:85], v[74:75], v[80:81] op_sel_hi:[1,0]
	v_pk_mul_f32 v[74:75], v[72:73], v[80:81] op_sel_hi:[1,0]
	v_cvt_pk_bf16_f32 v72, v76, v77
	v_cvt_pk_bf16_f32 v73, v78, v79
	v_pk_mul_f32 v[68:69], v[68:69], v[80:81] op_sel_hi:[1,0]
	v_cvt_pk_bf16_f32 v74, v74, v75
	v_cvt_pk_bf16_f32 v75, v84, v85
	global_store_dwordx4 v[82:83], v[72:75], off
	v_pk_mul_f32 v[70:71], v[70:71], v[80:81] op_sel_hi:[1,0]
	s_nop 0
	v_pk_mul_f32 v[72:73], v[66:67], v[80:81] op_sel_hi:[1,0]
	v_pk_mul_f32 v[66:67], v[64:65], v[80:81] op_sel_hi:[1,0]
	v_cvt_pk_bf16_f32 v64, v68, v69
	v_fmamk_f32 v68, v232, 0x39800000, v152
	v_rsq_f32_e32 v68, v68
	v_cvt_pk_bf16_f32 v65, v70, v71
	v_cvt_pk_bf16_f32 v66, v66, v67
	v_cvt_pk_bf16_f32 v67, v72, v73
	global_store_dwordx4 v[82:83], v[64:67], off offset:256
	s_nop 1
	v_mul_f32_e32 v64, v174, v68
	v_pk_mul_f32 v[60:61], v[60:61], v[64:65] op_sel_hi:[1,0]
	v_pk_mul_f32 v[68:69], v[58:59], v[64:65] op_sel_hi:[1,0]
	v_pk_mul_f32 v[58:59], v[56:57], v[64:65] op_sel_hi:[1,0]
	v_cvt_pk_bf16_f32 v56, v60, v61
	v_add_co_u32_e32 v60, vcc, s69, v144
	v_pk_mul_f32 v[62:63], v[62:63], v[64:65] op_sel_hi:[1,0]
	s_nop 0
	v_addc_co_u32_e32 v61, vcc, 0, v145, vcc
	v_cvt_pk_bf16_f32 v57, v62, v63
	v_pk_mul_f32 v[52:53], v[52:53], v[64:65] op_sel_hi:[1,0]
	v_cvt_pk_bf16_f32 v58, v58, v59
	v_cvt_pk_bf16_f32 v59, v68, v69
	global_store_dwordx4 v[60:61], v[56:59], off
	v_lshl_add_u64 v[66:67], v[144:145], 0, s[4:5]
	v_pk_mul_f32 v[54:55], v[54:55], v[64:65] op_sel_hi:[1,0]
	v_pk_mul_f32 v[56:57], v[50:51], v[64:65] op_sel_hi:[1,0]
	v_pk_mul_f32 v[50:51], v[48:49], v[64:65] op_sel_hi:[1,0]
	v_cvt_pk_bf16_f32 v48, v52, v53
	v_fmamk_f32 v52, v233, 0x39800000, v152
	v_rsq_f32_e32 v52, v52
	v_cvt_pk_bf16_f32 v49, v54, v55
	v_cvt_pk_bf16_f32 v50, v50, v51
	v_cvt_pk_bf16_f32 v51, v56, v57
	global_store_dwordx4 v[66:67], v[48:51], off offset:256
	s_nop 1
	v_mul_f32_e32 v48, v174, v52
	v_pk_mul_f32 v[44:45], v[44:45], v[48:49] op_sel_hi:[1,0]
	v_pk_mul_f32 v[52:53], v[42:43], v[48:49] op_sel_hi:[1,0]
	v_pk_mul_f32 v[42:43], v[40:41], v[48:49] op_sel_hi:[1,0]
	v_cvt_pk_bf16_f32 v40, v44, v45
	v_add_co_u32_e32 v44, vcc, s70, v144
	v_pk_mul_f32 v[46:47], v[46:47], v[48:49] op_sel_hi:[1,0]
	s_nop 0
	v_addc_co_u32_e32 v45, vcc, 0, v145, vcc
	v_cvt_pk_bf16_f32 v41, v46, v47
	v_pk_mul_f32 v[36:37], v[36:37], v[48:49] op_sel_hi:[1,0]
	v_cvt_pk_bf16_f32 v42, v42, v43
	v_cvt_pk_bf16_f32 v43, v52, v53
	global_store_dwordx4 v[44:45], v[40:43], off
	v_lshl_add_u64 v[50:51], v[144:145], 0, s[14:15]
	v_pk_mul_f32 v[38:39], v[38:39], v[48:49] op_sel_hi:[1,0]
	v_pk_mul_f32 v[40:41], v[34:35], v[48:49] op_sel_hi:[1,0]
	v_pk_mul_f32 v[34:35], v[32:33], v[48:49] op_sel_hi:[1,0]
	v_cvt_pk_bf16_f32 v32, v36, v37
	v_fmamk_f32 v36, v234, 0x39800000, v152
	v_rsq_f32_e32 v36, v36
	v_cvt_pk_bf16_f32 v33, v38, v39
	v_cvt_pk_bf16_f32 v34, v34, v35
	v_cvt_pk_bf16_f32 v35, v40, v41
	global_store_dwordx4 v[50:51], v[32:35], off offset:256
	s_nop 1
	v_mul_f32_e32 v32, v174, v36
	v_pk_mul_f32 v[28:29], v[28:29], v[32:33] op_sel_hi:[1,0]
	v_pk_mul_f32 v[36:37], v[26:27], v[32:33] op_sel_hi:[1,0]
	v_pk_mul_f32 v[26:27], v[24:25], v[32:33] op_sel_hi:[1,0]
	v_cvt_pk_bf16_f32 v24, v28, v29
	v_add_co_u32_e32 v28, vcc, s71, v144
	v_pk_mul_f32 v[30:31], v[30:31], v[32:33] op_sel_hi:[1,0]
	s_nop 0
	v_addc_co_u32_e32 v29, vcc, 0, v145, vcc
	v_cvt_pk_bf16_f32 v25, v30, v31
	v_pk_mul_f32 v[20:21], v[20:21], v[32:33] op_sel_hi:[1,0]
	v_cvt_pk_bf16_f32 v26, v26, v27
	v_cvt_pk_bf16_f32 v27, v36, v37
	global_store_dwordx4 v[28:29], v[24:27], off
	v_lshl_add_u64 v[34:35], v[144:145], 0, s[16:17]
	v_pk_mul_f32 v[22:23], v[22:23], v[32:33] op_sel_hi:[1,0]
	v_pk_mul_f32 v[24:25], v[18:19], v[32:33] op_sel_hi:[1,0]
	v_pk_mul_f32 v[18:19], v[16:17], v[32:33] op_sel_hi:[1,0]
	v_cvt_pk_bf16_f32 v16, v20, v21
	v_fmamk_f32 v20, v235, 0x39800000, v152
	v_rsq_f32_e32 v20, v20
	v_cvt_pk_bf16_f32 v17, v22, v23
	v_cvt_pk_bf16_f32 v18, v18, v19
	v_cvt_pk_bf16_f32 v19, v24, v25
	global_store_dwordx4 v[34:35], v[16:19], off offset:256
	s_nop 1
	v_mul_f32_e32 v16, v174, v20
	v_pk_mul_f32 v[12:13], v[12:13], v[16:17] op_sel_hi:[1,0]
	v_pk_mul_f32 v[20:21], v[10:11], v[16:17] op_sel_hi:[1,0]
	v_pk_mul_f32 v[10:11], v[8:9], v[16:17] op_sel_hi:[1,0]
	v_cvt_pk_bf16_f32 v8, v12, v13
	v_add_co_u32_e32 v12, vcc, s72, v144
	v_pk_mul_f32 v[14:15], v[14:15], v[16:17] op_sel_hi:[1,0]
	s_nop 0
	v_addc_co_u32_e32 v13, vcc, 0, v145, vcc
	v_cvt_pk_bf16_f32 v9, v14, v15
	v_lshl_add_u64 v[18:19], v[144:145], 0, s[18:19]
	v_cvt_pk_bf16_f32 v10, v10, v11
	v_cvt_pk_bf16_f32 v11, v20, v21
	global_store_dwordx4 v[12:13], v[8:11], off
	s_andn2_b64 vcc, exec, s[0:1]
	s_mov_b64 s[0:1], -1
	v_pk_mul_f32 v[8:9], v[2:3], v[16:17] op_sel_hi:[1,0]
	v_pk_mul_f32 v[2:3], v[0:1], v[16:17] op_sel_hi:[1,0]
	v_pk_mul_f32 v[6:7], v[6:7], v[16:17] op_sel_hi:[1,0]
	v_pk_mul_f32 v[4:5], v[4:5], v[16:17] op_sel_hi:[1,0]
	s_nop 0
	v_cvt_pk_bf16_f32 v0, v4, v5
	v_cvt_pk_bf16_f32 v1, v6, v7
	v_cvt_pk_bf16_f32 v2, v2, v3
	v_cvt_pk_bf16_f32 v3, v8, v9
	global_store_dwordx4 v[18:19], v[0:3], off offset:256
	s_cbranch_vccnz .LBB0_180
.Lp2_join:
	s_andn2_b64 vcc, exec, s[6:7]
	s_cbranch_vccnz .LBB0_179
	s_barrier
	s_branch .LBB0_179
.Lp2_vepi:
	v_mbcnt_lo_u32_b32 v144, -1, 0
	v_mbcnt_hi_u32_b32 v144, -1, v144
	s_and_b32 s21, s89, 3
	s_lshr_b32 s23, s89, 2
	v_and_b32_e32 v145, 15, v144
	v_lshrrev_b32_e32 v154, 4, v144
	s_lshl_b32 s30, s28, 8
	s_lshl_b32 s31, s21, 5
	s_add_i32 s30, s30, s31
	v_lshl_add_u32 v155, v154, 3, s30
	v_lshlrev_b32_e32 v155, 2, v155
	global_load_dwordx4 v[226:229], v155, s[8:9]
	global_load_dwordx4 v[230:233], v155, s[8:9] offset:16
	global_load_dwordx4 v[234:237], v155, s[8:9] offset:512
	global_load_dwordx4 v[238:241], v155, s[8:9] offset:528
	s_sub_i32 s30, s29, 32
	s_lshl_b32 s30, s30, 8
	s_lshl_b32 s31, s28, 2
	s_add_i32 s30, s30, s31
	s_lshr_b32 s31, s21, 1
	s_add_i32 s30, s30, s31
	s_lshl_b32 s30, s30, 15
	s_add_u32 s30, s30, 0x20200000
	s_addc_u32 s31, 0, 0
	s_add_u32 s30, s66, s30
	s_addc_u32 s31, s67, s31
	s_and_b32 s21, s21, 1
	s_lshl_b32 s21, s21, 2
	v_and_b32_e32 v156, 1, v154
	v_lshlrev_b32_e32 v156, 1, v156
	v_or_b32_e32 v156, s21, v156
	v_bfe_u32 v157, v144, 1, 3
	v_xor_b32_e32 v156, v156, v157
	v_lshlrev_b32_e32 v156, 4, v156
	v_lshrrev_b32_e32 v157, 1, v154
	v_lshl_add_u32 v156, v157, 3, v156
	v_lshl_add_u32 v156, v145, 7, v156
	s_lshl_b32 s23, s23, 13
	v_add_u32_e32 v156, s23, v156
	s_waitcnt vmcnt(0)
	v_fmamk_f32 v226, v226, 0x39800000, v152
	v_fmamk_f32 v227, v227, 0x39800000, v152
	v_fmamk_f32 v228, v228, 0x39800000, v152
	v_fmamk_f32 v229, v229, 0x39800000, v152
	v_fmamk_f32 v230, v230, 0x39800000, v152
	v_fmamk_f32 v231, v231, 0x39800000, v152
	v_fmamk_f32 v232, v232, 0x39800000, v152
	v_fmamk_f32 v233, v233, 0x39800000, v152
	v_fmamk_f32 v234, v234, 0x39800000, v152
	v_fmamk_f32 v235, v235, 0x39800000, v152
	v_fmamk_f32 v236, v236, 0x39800000, v152
	v_fmamk_f32 v237, v237, 0x39800000, v152
	v_fmamk_f32 v238, v238, 0x39800000, v152
	v_fmamk_f32 v239, v239, 0x39800000, v152
	v_fmamk_f32 v240, v240, 0x39800000, v152
	v_fmamk_f32 v241, v241, 0x39800000, v152
	v_rsq_f32_e32 v226, v226
	v_rsq_f32_e32 v227, v227
	v_rsq_f32_e32 v228, v228
	v_rsq_f32_e32 v229, v229
	v_rsq_f32_e32 v230, v230
	v_rsq_f32_e32 v231, v231
	v_rsq_f32_e32 v232, v232
	v_rsq_f32_e32 v233, v233
	v_rsq_f32_e32 v234, v234
	v_rsq_f32_e32 v235, v235
	v_rsq_f32_e32 v236, v236
	v_rsq_f32_e32 v237, v237
	v_rsq_f32_e32 v238, v238
	v_rsq_f32_e32 v239, v239
	v_rsq_f32_e32 v240, v240
	v_rsq_f32_e32 v241, v241
	s_nop 0
	v_mul_f32_e32 v124, v124, v226
	v_mul_f32_e32 v125, v125, v227
	v_mul_f32_e32 v126, v126, v228
	v_mul_f32_e32 v127, v127, v229
	v_mul_f32_e32 v120, v120, v230
	v_mul_f32_e32 v121, v121, v231
	v_mul_f32_e32 v122, v122, v232
	v_mul_f32_e32 v123, v123, v233
	v_cvt_pk_bf16_f32 v124, v124, v125
	v_cvt_pk_bf16_f32 v125, v126, v127
	v_cvt_pk_bf16_f32 v120, v120, v121
	v_cvt_pk_bf16_f32 v121, v122, v123
	v_mov_b32_e32 v157, v156
	v_xor_b32_e32 v158, 16, v157
	global_store_dwordx2 v157, v[124:125], s[30:31]
	global_store_dwordx2 v158, v[120:121], s[30:31]
	v_mul_f32_e32 v108, v108, v234
	v_mul_f32_e32 v109, v109, v235
	v_mul_f32_e32 v110, v110, v236
	v_mul_f32_e32 v111, v111, v237
	v_mul_f32_e32 v100, v100, v238
	v_mul_f32_e32 v101, v101, v239
	v_mul_f32_e32 v102, v102, v240
	v_mul_f32_e32 v103, v103, v241
	v_cvt_pk_bf16_f32 v108, v108, v109
	v_cvt_pk_bf16_f32 v109, v110, v111
	v_cvt_pk_bf16_f32 v100, v100, v101
	v_cvt_pk_bf16_f32 v101, v102, v103
	v_add_u32_e32 v157, 0x10000, v156
	v_xor_b32_e32 v158, 16, v157
	global_store_dwordx2 v157, v[108:109], s[30:31]
	global_store_dwordx2 v158, v[100:101], s[30:31]
	v_mul_f32_e32 v116, v116, v226
	v_mul_f32_e32 v117, v117, v227
	v_mul_f32_e32 v118, v118, v228
	v_mul_f32_e32 v119, v119, v229
	v_mul_f32_e32 v112, v112, v230
	v_mul_f32_e32 v113, v113, v231
	v_mul_f32_e32 v114, v114, v232
	v_mul_f32_e32 v115, v115, v233
	v_cvt_pk_bf16_f32 v116, v116, v117
	v_cvt_pk_bf16_f32 v117, v118, v119
	v_cvt_pk_bf16_f32 v112, v112, v113
	v_cvt_pk_bf16_f32 v113, v114, v115
	v_add_u32_e32 v157, 0x800, v156
	v_xor_b32_e32 v158, 16, v157
	global_store_dwordx2 v157, v[116:117], s[30:31]
	global_store_dwordx2 v158, v[112:113], s[30:31]
	v_mul_f32_e32 v92, v92, v234
	v_mul_f32_e32 v93, v93, v235
	v_mul_f32_e32 v94, v94, v236
	v_mul_f32_e32 v95, v95, v237
	v_mul_f32_e32 v88, v88, v238
	v_mul_f32_e32 v89, v89, v239
	v_mul_f32_e32 v90, v90, v240
	v_mul_f32_e32 v91, v91, v241
	v_cvt_pk_bf16_f32 v92, v92, v93
	v_cvt_pk_bf16_f32 v93, v94, v95
	v_cvt_pk_bf16_f32 v88, v88, v89
	v_cvt_pk_bf16_f32 v89, v90, v91
	v_add_u32_e32 v157, 0x10800, v156
	v_xor_b32_e32 v158, 16, v157
	global_store_dwordx2 v157, v[92:93], s[30:31]
	global_store_dwordx2 v158, v[88:89], s[30:31]
	v_mul_f32_e32 v104, v104, v226
	v_mul_f32_e32 v105, v105, v227
	v_mul_f32_e32 v106, v106, v228
	v_mul_f32_e32 v107, v107, v229
	v_mul_f32_e32 v96, v96, v230
	v_mul_f32_e32 v97, v97, v231
	v_mul_f32_e32 v98, v98, v232
	v_mul_f32_e32 v99, v99, v233
	v_cvt_pk_bf16_f32 v104, v104, v105
	v_cvt_pk_bf16_f32 v105, v106, v107
	v_cvt_pk_bf16_f32 v96, v96, v97
	v_cvt_pk_bf16_f32 v97, v98, v99
	v_add_u32_e32 v157, 0x1000, v156
	v_xor_b32_e32 v158, 16, v157
	global_store_dwordx2 v157, v[104:105], s[30:31]
	global_store_dwordx2 v158, v[96:97], s[30:31]
	v_mul_f32_e32 v84, v84, v234
	v_mul_f32_e32 v85, v85, v235
	v_mul_f32_e32 v86, v86, v236
	v_mul_f32_e32 v87, v87, v237
	v_mul_f32_e32 v80, v80, v238
	v_mul_f32_e32 v81, v81, v239
	v_mul_f32_e32 v82, v82, v240
	v_mul_f32_e32 v83, v83, v241
	v_cvt_pk_bf16_f32 v84, v84, v85
	v_cvt_pk_bf16_f32 v85, v86, v87
	v_cvt_pk_bf16_f32 v80, v80, v81
	v_cvt_pk_bf16_f32 v81, v82, v83
	v_add_u32_e32 v157, 0x11000, v156
	v_xor_b32_e32 v158, 16, v157
	global_store_dwordx2 v157, v[84:85], s[30:31]
	global_store_dwordx2 v158, v[80:81], s[30:31]
	v_mul_f32_e32 v76, v76, v226
	v_mul_f32_e32 v77, v77, v227
	v_mul_f32_e32 v78, v78, v228
	v_mul_f32_e32 v79, v79, v229
	v_mul_f32_e32 v72, v72, v230
	v_mul_f32_e32 v73, v73, v231
	v_mul_f32_e32 v74, v74, v232
	v_mul_f32_e32 v75, v75, v233
	v_cvt_pk_bf16_f32 v76, v76, v77
	v_cvt_pk_bf16_f32 v77, v78, v79
	v_cvt_pk_bf16_f32 v72, v72, v73
	v_cvt_pk_bf16_f32 v73, v74, v75
	v_add_u32_e32 v157, 0x1800, v156
	v_xor_b32_e32 v158, 16, v157
	global_store_dwordx2 v157, v[76:77], s[30:31]
	global_store_dwordx2 v158, v[72:73], s[30:31]
	v_mul_f32_e32 v68, v68, v234
	v_mul_f32_e32 v69, v69, v235
	v_mul_f32_e32 v70, v70, v236
	v_mul_f32_e32 v71, v71, v237
	v_mul_f32_e32 v64, v64, v238
	v_mul_f32_e32 v65, v65, v239
	v_mul_f32_e32 v66, v66, v240
	v_mul_f32_e32 v67, v67, v241
	v_cvt_pk_bf16_f32 v68, v68, v69
	v_cvt_pk_bf16_f32 v69, v70, v71
	v_cvt_pk_bf16_f32 v64, v64, v65
	v_cvt_pk_bf16_f32 v65, v66, v67
	v_add_u32_e32 v157, 0x11800, v156
	v_xor_b32_e32 v158, 16, v157
	global_store_dwordx2 v157, v[68:69], s[30:31]
	global_store_dwordx2 v158, v[64:65], s[30:31]
	v_mul_f32_e32 v60, v60, v226
	v_mul_f32_e32 v61, v61, v227
	v_mul_f32_e32 v62, v62, v228
	v_mul_f32_e32 v63, v63, v229
	v_mul_f32_e32 v56, v56, v230
	v_mul_f32_e32 v57, v57, v231
	v_mul_f32_e32 v58, v58, v232
	v_mul_f32_e32 v59, v59, v233
	v_cvt_pk_bf16_f32 v60, v60, v61
	v_cvt_pk_bf16_f32 v61, v62, v63
	v_cvt_pk_bf16_f32 v56, v56, v57
	v_cvt_pk_bf16_f32 v57, v58, v59
	v_add_u32_e32 v157, 0x4000, v156
	v_xor_b32_e32 v158, 16, v157
	global_store_dwordx2 v157, v[60:61], s[30:31]
	global_store_dwordx2 v158, v[56:57], s[30:31]
	v_mul_f32_e32 v52, v52, v234
	v_mul_f32_e32 v53, v53, v235
	v_mul_f32_e32 v54, v54, v236
	v_mul_f32_e32 v55, v55, v237
	v_mul_f32_e32 v48, v48, v238
	v_mul_f32_e32 v49, v49, v239
	v_mul_f32_e32 v50, v50, v240
	v_mul_f32_e32 v51, v51, v241
	v_cvt_pk_bf16_f32 v52, v52, v53
	v_cvt_pk_bf16_f32 v53, v54, v55
	v_cvt_pk_bf16_f32 v48, v48, v49
	v_cvt_pk_bf16_f32 v49, v50, v51
	v_add_u32_e32 v157, 0x14000, v156
	v_xor_b32_e32 v158, 16, v157
	global_store_dwordx2 v157, v[52:53], s[30:31]
	global_store_dwordx2 v158, v[48:49], s[30:31]
	v_mul_f32_e32 v44, v44, v226
	v_mul_f32_e32 v45, v45, v227
	v_mul_f32_e32 v46, v46, v228
	v_mul_f32_e32 v47, v47, v229
	v_mul_f32_e32 v40, v40, v230
	v_mul_f32_e32 v41, v41, v231
	v_mul_f32_e32 v42, v42, v232
	v_mul_f32_e32 v43, v43, v233
	v_cvt_pk_bf16_f32 v44, v44, v45
	v_cvt_pk_bf16_f32 v45, v46, v47
	v_cvt_pk_bf16_f32 v40, v40, v41
	v_cvt_pk_bf16_f32 v41, v42, v43
	v_add_u32_e32 v157, 0x4800, v156
	v_xor_b32_e32 v158, 16, v157
	global_store_dwordx2 v157, v[44:45], s[30:31]
	global_store_dwordx2 v158, v[40:41], s[30:31]
	v_mul_f32_e32 v36, v36, v234
	v_mul_f32_e32 v37, v37, v235
	v_mul_f32_e32 v38, v38, v236
	v_mul_f32_e32 v39, v39, v237
	v_mul_f32_e32 v32, v32, v238
	v_mul_f32_e32 v33, v33, v239
	v_mul_f32_e32 v34, v34, v240
	v_mul_f32_e32 v35, v35, v241
	v_cvt_pk_bf16_f32 v36, v36, v37
	v_cvt_pk_bf16_f32 v37, v38, v39
	v_cvt_pk_bf16_f32 v32, v32, v33
	v_cvt_pk_bf16_f32 v33, v34, v35
	v_add_u32_e32 v157, 0x14800, v156
	v_xor_b32_e32 v158, 16, v157
	global_store_dwordx2 v157, v[36:37], s[30:31]
	global_store_dwordx2 v158, v[32:33], s[30:31]
	v_mul_f32_e32 v28, v28, v226
	v_mul_f32_e32 v29, v29, v227
	v_mul_f32_e32 v30, v30, v228
	v_mul_f32_e32 v31, v31, v229
	v_mul_f32_e32 v24, v24, v230
	v_mul_f32_e32 v25, v25, v231
	v_mul_f32_e32 v26, v26, v232
	v_mul_f32_e32 v27, v27, v233
	v_cvt_pk_bf16_f32 v28, v28, v29
	v_cvt_pk_bf16_f32 v29, v30, v31
	v_cvt_pk_bf16_f32 v24, v24, v25
	v_cvt_pk_bf16_f32 v25, v26, v27
	v_add_u32_e32 v157, 0x5000, v156
	v_xor_b32_e32 v158, 16, v157
	global_store_dwordx2 v157, v[28:29], s[30:31]
	global_store_dwordx2 v158, v[24:25], s[30:31]
	v_mul_f32_e32 v20, v20, v234
	v_mul_f32_e32 v21, v21, v235
	v_mul_f32_e32 v22, v22, v236
	v_mul_f32_e32 v23, v23, v237
	v_mul_f32_e32 v16, v16, v238
	v_mul_f32_e32 v17, v17, v239
	v_mul_f32_e32 v18, v18, v240
	v_mul_f32_e32 v19, v19, v241
	v_cvt_pk_bf16_f32 v20, v20, v21
	v_cvt_pk_bf16_f32 v21, v22, v23
	v_cvt_pk_bf16_f32 v16, v16, v17
	v_cvt_pk_bf16_f32 v17, v18, v19
	v_add_u32_e32 v157, 0x15000, v156
	v_xor_b32_e32 v158, 16, v157
	global_store_dwordx2 v157, v[20:21], s[30:31]
	global_store_dwordx2 v158, v[16:17], s[30:31]
	v_mul_f32_e32 v12, v12, v226
	v_mul_f32_e32 v13, v13, v227
	v_mul_f32_e32 v14, v14, v228
	v_mul_f32_e32 v15, v15, v229
	v_mul_f32_e32 v8, v8, v230
	v_mul_f32_e32 v9, v9, v231
	v_mul_f32_e32 v10, v10, v232
	v_mul_f32_e32 v11, v11, v233
	v_cvt_pk_bf16_f32 v12, v12, v13
	v_cvt_pk_bf16_f32 v13, v14, v15
	v_cvt_pk_bf16_f32 v8, v8, v9
	v_cvt_pk_bf16_f32 v9, v10, v11
	v_add_u32_e32 v157, 0x5800, v156
	v_xor_b32_e32 v158, 16, v157
	global_store_dwordx2 v157, v[12:13], s[30:31]
	global_store_dwordx2 v158, v[8:9], s[30:31]
	v_mul_f32_e32 v4, v4, v234
	v_mul_f32_e32 v5, v5, v235
	v_mul_f32_e32 v6, v6, v236
	v_mul_f32_e32 v7, v7, v237
	v_mul_f32_e32 v0, v0, v238
	v_mul_f32_e32 v1, v1, v239
	v_mul_f32_e32 v2, v2, v240
	v_mul_f32_e32 v3, v3, v241
	v_cvt_pk_bf16_f32 v4, v4, v5
	v_cvt_pk_bf16_f32 v5, v6, v7
	v_cvt_pk_bf16_f32 v0, v0, v1
	v_cvt_pk_bf16_f32 v1, v2, v3
	v_add_u32_e32 v157, 0x15800, v156
	v_xor_b32_e32 v158, 16, v157
	global_store_dwordx2 v157, v[4:5], s[30:31]
	global_store_dwordx2 v158, v[0:1], s[30:31]
	s_andn2_b64 vcc, exec, s[0:1]
	s_mov_b64 s[0:1], -1
	s_cbranch_vccnz .LBB0_180
	s_branch .Lp2_join

.LBB0_254:
	s_cmp_lt_i32 s59, 1
	s_cbranch_scc1 .LBB0_360
	s_add_u32 s3, s66, 0x20200000
	v_writelane_b32 v254, s90, 11
	s_addc_u32 s6, s67, 0
	s_ashr_i32 s0, s88, 4
	v_writelane_b32 v254, s91, 12
	s_and_b32 s0, s0, -2
	v_writelane_b32 v254, s0, 13
	v_writelane_b32 v254, s88, 14
	s_and_b32 s0, s88, 31
	v_writelane_b32 v254, s0, 15
	s_and_b32 s0, s87, 0xffffffc0
	v_mov_b32_e32 v0, 0x3e4ccccd
	v_writelane_b32 v254, s0, 16
	s_lshl_b32 s0, s0, 2
	v_add_f32_e32 v0, s1, v0
	s_add_i32 s96, s0, 0
	s_add_i32 s0, s89, -4
	s_lshl_b32 s1, s89, 7
	s_lshl_b32 s4, s89, 18
	s_bfe_u32 s7, s87, 0x20006
	s_lshl_b32 s9, s0, 13
	s_and_b32 s1, s1, 0xffffff00
	s_and_b32 s4, s4, 0x40000
	s_lshl_b32 s0, s0, 13
	s_lshr_b32 s8, s87, 8
	s_lshl_b32 s14, s7, 5
	s_add_i32 s96, s96, 0x20200
	s_add_i32 s10, s1, s4
	s_lshl_b32 s11, s89, 13
	s_add_i32 s12, s0, 0x8000
	s_cmpk_lt_u32 s87, 0x100
	s_cselect_b64 s[0:1], -1, 0
	s_and_b64 s[4:5], s[0:1], exec
	s_movk_i32 s5, 0x400
	v_writelane_b32 v254, s89, 17
	s_cselect_b32 s4, s11, s12
	s_cselect_b32 s11, 0x8000, s5
	s_mov_b32 s5, 0x10000
	v_writelane_b32 v254, s87, 18
	s_cselect_b32 s12, s5, 0x800
	s_mov_b32 s5, 0x18000
	s_cselect_b32 s20, 0xc0, 0
	s_cselect_b32 s16, s5, 0xc00
	s_mov_b32 s5, 0x20000
	v_writelane_b32 v254, s20, 19
	s_cselect_b32 s20, 0x80, 0
	s_cselect_b32 s17, s5, 0x1000
	s_mov_b32 s5, 0x28000
	v_writelane_b32 v254, s20, 20
	s_cselect_b32 s20, 64, 0
	s_cselect_b32 s18, s5, 0x1400
	s_mov_b32 s5, 0x30000
	v_writelane_b32 v254, s20, 21
	s_cselect_b32 s19, s5, 0x1800
	s_mov_b32 s5, 0x38000
	s_cselect_b32 s63, s95, s6
	v_writelane_b32 v254, s94, 22
	s_cselect_b32 s5, s5, 0x1c00
	s_cselect_b32 s93, s10, s9
	v_writelane_b32 v254, s95, 23
	s_cselect_b32 s62, s94, s3
	s_add_i32 s97, s4, 0
	s_lshl_b32 s4, s8, 14
	v_writelane_b32 v254, s4, 24
	s_lshl_b32 s4, s7, 15
	s_add_i32 s75, s97, 0x400
	s_add_i32 s68, s97, 0x800
	s_add_i32 s69, s97, 0xc00
	s_add_i32 s78, s97, 0x1000
	s_add_i32 s79, s97, 0x1400
	s_add_i32 s54, s97, 0x1800
	s_add_i32 s55, s97, 0x1c00
	s_lshl_b32 s3, s8, 7
	s_add_i32 s71, s97, 0x10000
	s_add_i32 s92, s97, 0x10400
	s_add_i32 s70, s97, 0x10800
	s_add_i32 s80, s97, 0x10c00
	s_add_i32 s81, s97, 0x11000
	s_add_i32 s50, s97, 0x11400
	s_add_i32 s51, s97, 0x11800
	s_add_i32 s94, s97, 0x11c00
	s_add_i32 s95, s4, 0
	s_cmp_eq_u32 s8, 1
	s_cselect_b64 s[6:7], -1, 0
	v_writelane_b32 v254, s6, 25
	s_lshl_b32 s4, s8, 4
	s_mov_b32 s15, 0
	v_writelane_b32 v254, s7, 26
	v_writelane_b32 v254, s4, 27
	v_writelane_b32 v254, s14, 28
	s_add_i32 s4, s14, 0xffffffa5
	v_writelane_b32 v254, s4, 29
	v_writelane_b32 v254, s5, 30
	s_add_i32 s4, s93, s5
	v_writelane_b32 v254, s4, 31
	v_writelane_b32 v254, s16, 32
	s_add_i32 s4, s93, s16
	v_writelane_b32 v254, s4, 33
	v_writelane_b32 v254, s19, 34
	s_add_i32 s4, s93, s19
	v_writelane_b32 v254, s4, 35
	v_writelane_b32 v254, s12, 36
	s_add_i32 s4, s93, s12
	v_writelane_b32 v254, s4, 37
	v_writelane_b32 v254, s18, 38
	s_add_i32 s4, s93, s18
	v_writelane_b32 v254, s4, 39
	v_writelane_b32 v254, s11, 40
	s_add_i32 s4, s93, s11
	v_writelane_b32 v254, s4, 41
	v_writelane_b32 v254, s17, 42
	s_add_i32 s4, s93, s17
	v_xor_b32_e32 v210, 0x80000000, v0
	v_writelane_b32 v254, s4, 43
	s_lshl_b32 s14, s3, 1
	v_mov_b32_e32 v212, v210
	v_mov_b32_e32 v213, v210
	v_mov_b32_e32 v1, 0
	s_mov_b32 s74, 0x41000000
	v_mov_b32_e32 v214, 0x3727c5ac
	v_mov_b32_e32 v215, 0x41b17218
	v_mov_b32_e32 v216, 0xff800000
	v_writelane_b32 v254, s14, 44
	s_mov_b32 s72, s15
	s_nop 0
	v_writelane_b32 v254, s15, 45
	s_branch .LBB0_257

.Lat_entry:
	s_mov_b32 s92, m0
	s_add_i32 s71, s97, 0x10000
	s_mov_b32 s70, 0
	s_movk_i32 s81, 0x7f
	s_mov_b32 s80, 0x20000
	s_cmp_lg_u64 s[0:1], 0
	s_mov_b32 s100, 0x8000
	s_cselect_b32 s100, 0x80000, s100
	s_add_i32 s51, s90, s100
	s_add_u32 s50, s62, s51
	s_addc_u32 s51, s63, 0
	s_mov_b32 s84, 1
	s_mov_b32 s94, 0xff800000
	v_mov_b32_e32 v246, 0
	v_mov_b32_e32 v247, 0
	v_mov_b32_e32 v248, 0
	v_mov_b32_e32 v249, 0
	v_mov_b32_e32 v250, 0
	v_mov_b32_e32 v251, 0
	v_mov_b32_e32 v252, 0
	v_mov_b32_e32 v253, 0
	v_readlane_b32 s4, v254, 24
	v_and_b32_e32 v234, 15, v211
	v_lshrrev_b32_e32 v235, 4, v211
	v_xor_b32_e32 v236, v234, v235
	v_lshlrev_b32_e32 v236, 4, v236
	v_lshl_add_u32 v236, v234, 8, v236
	v_add_u32_e32 v221, s4, v236
	v_lshlrev_b32_e32 v237, 2, v235
	v_sub_u32_e32 v237, v234, v237
	v_add_u32_e32 v223, s3, v237
	v_bfe_u32 v237, v211, 1, 3
	v_xor_b32_e32 v237, v235, v237
	v_lshlrev_b32_e32 v237, 4, v237
	v_lshl_add_u32 v237, v234, 7, v237
	v_add_u32_e32 v222, 0x8000, v237
	v_mov_b32_e32 v243, v233
	v_mov_b32_e32 v244, 0
	v_xor_b32_e32 v234, s70, v221
	v_xor_b32_e32 v235, 64, v234
	v_xor_b32_e32 v236, 0x80, v234
	v_xor_b32_e32 v237, 0xc0, v234
	s_lshl_b64 s[98:99], s[82:83], 1
	s_add_u32 s98, s48, s98
	s_addc_u32 s99, s49, s99
	v_readlane_b32 s4, v254, 27
	s_nop 1
	v_add_u32_e32 v245, s4, v218
	v_add_u32_e32 v245, s3, v245
	v_lshlrev_b32_e32 v245, 13, v245
	v_lshl_add_u32 v245, v217, 4, v245
